# ssm pass-3: the second half-chunk's 8 gelu stores are held in registers and issued after the next chunk's loads, so the chunk-top wait is vmcnt(8) and never sits behind a just-issued store
# baseline (speedup 1.0000x reference)
; __device__ __forceinline__ unsigned f2bf(float f) { unsigned u = __builtin_bit_cast(unsigned, f); return (u + 0x7fffu + ((u >> 16) & 1u)) >> 16; }
; __device__ __forceinline__ float gelu_tanh(float v) { const float z = 0.7978845608028654f * (v + 0.044715f * v * v * v); return v * (1.0f - 1.0f / (1.0f + __expf(2.0f * z))); }
; template <int PASS> __device__ __forceinline__ void ssm_phase(int j, LAS unsigned char* lds, int lane, int wave) { KARGS;
;     ...
;                         for (int r = 0; r < 4; ++r) { const int l = 32 * half + 16 * lt + 4 * fq + r; const size_t t = (size_t)(64 * c + l);
;                             const float v = y[r] + dd * X[t * D + ch] * rsL[l];
;                             GL[t * D + ch] = (bf16_t)f2bf(gelu_tanh(v)); }
.Lssm3_task_fl:
	global_store_short_d16_hi v246, v212, s[64:65]
	global_store_short_d16_hi v247, v213, s[64:65]
	global_store_short_d16_hi v248, v214, s[64:65]
	global_store_short_d16_hi v249, v215, s[64:65]
	global_store_short_d16_hi v250, v216, s[64:65]
	global_store_short_d16_hi v251, v217, s[64:65]
	global_store_short_d16_hi v252, v244, s[64:65]
	global_store_short_d16_hi v253, v245, s[64:65]

; #define LAS __attribute__((address_space(3)))
; __device__ __forceinline__ unsigned pk2(float lo, float hi) { const f32x2 v = {lo, hi}; const bf16x2_t b = __builtin_convertvector(v, bf16x2_t); return __builtin_bit_cast(unsigned, b); }
; #define CBAR() asm volatile("s_waitcnt lgkmcnt(0)" ::: "memory")
; template <int PASS> __device__ __forceinline__ void ssm_phase(int j, LAS unsigned char* lds, int lane, int wave) { KARGS;
;     ...
;             { const int t = 64 * c + lane; float ssq = 0.f;
; #pragma unroll
;               for (int q = 0; q < 8; ++q) { const f32x4 v = *(const f32x4*)(rsp + (size_t)t * 64 + 4 * q); ssq += (v[0] + v[1]) + (v[2] + v[3]); }
;               rsL[lane] = rsqrtf(ssq * (1.0f / D) + EPS); }
;     ...
;                         if (PASS == 3) *(LAS unsigned*)(hL + (l8 + q) * 256 + ((((p >> 2) ^ ((l8 + q) & 15))) << 4) + (p & 3) * 4) = pk2(hr, hi);
;                     }
;                 }
;                 CBAR();
;                 if (PASS == 3) {
; #pragma unroll
;                     for (int lt = 0; lt < 2; ++lt) {
;                         f32x4 y = {0.f, 0.f, 0.f, 0.f};
; #pragma unroll
;                         for (int ks = 0; ks < 4; ++ks) { const bf16x8 hf = *(const LAS bf16x8*)(hL + (16 * lt + fr) * 256 + (((4 * ks + fq) ^ fr) << 4)); y = __builtin_amdgcn_mfma_f32_16x16x32_bf16(hf, cf[ks], y, 0, 0, 0); }
;                         asm volatile("s_nop 15\n\ts_nop 15" : "+v"(y));
;                         const int ch = 16 * g + fr;
; #pragma unroll
;                         for (int r = 0; r < 4; ++r) { const int l = 32 * half + 16 * lt + 4 * fq + r; const size_t t = (size_t)(64 * c + l);
;                             const float v = y[r] + dd * X[t * D + ch] * rsL[l];
.LBB0_342:
	s_lshl_b32 s12, s53, 6
	v_or_b32_e32 v52, s12, v60
	v_ashrrev_i32_e32 v53, 31, v52
	v_lshlrev_b64 v[52:53], 8, v[52:53]
	v_lshl_add_u64 v[106:107], s[62:63], 0, v[52:53]
	global_load_dwordx4 v[52:55], v[106:107], off offset:48
	global_load_dwordx4 v[56:59], v[106:107], off offset:32
	global_load_dwordx4 v[98:101], v[106:107], off
	global_load_dwordx4 v[102:105], v[106:107], off offset:16
	s_or_b32 s13, s12, 16
	s_or_b32 s54, s12, 1
	s_or_b32 s55, s12, 2
	s_or_b32 s68, s12, 3
	s_or_b32 s77, s12, 17
	s_or_b32 s80, s12, 18
	s_or_b32 s81, s12, 19
	s_mov_b32 s70, 0
	s_mov_b64 s[4:5], -1
	global_load_dwordx4 v[140:143], v[106:107], off offset:112
	global_load_dwordx4 v[144:147], v[106:107], off offset:96
	global_load_dwordx4 v[148:151], v[106:107], off offset:80
	global_load_dwordx4 v[152:155], v[106:107], off offset:64
	v_add_u32_e32 v211, s15, v77
	v_xor_b32_e32 v195, 0, v63
	v_lshlrev_b32_e32 v195, 4, v195
	v_add3_u32 v195, s15, v195, v73
	v_xor_b32_e32 v196, 1, v63
	v_lshlrev_b32_e32 v196, 4, v196
	v_add3_u32 v196, s15, v196, v73
	v_xor_b32_e32 v197, 2, v63
	v_lshlrev_b32_e32 v197, 4, v197
	v_add3_u32 v197, s15, v197, v73
	v_xor_b32_e32 v198, 3, v63
	v_lshlrev_b32_e32 v198, 4, v198
	v_add3_u32 v198, s15, v198, v73
	v_xor_b32_e32 v199, 4, v63
	v_lshlrev_b32_e32 v199, 4, v199
	v_add3_u32 v199, s15, v199, v73
	v_xor_b32_e32 v200, 5, v63
	v_lshlrev_b32_e32 v200, 4, v200
	v_add3_u32 v200, s15, v200, v73
	v_xor_b32_e32 v201, 6, v63
	v_lshlrev_b32_e32 v201, 4, v201
	v_add3_u32 v201, s15, v201, v73
	v_xor_b32_e32 v202, 7, v63
	v_lshlrev_b32_e32 v202, 4, v202
	v_add3_u32 v202, s15, v202, v73
	v_xor_b32_e32 v203, 8, v63
	v_lshlrev_b32_e32 v203, 4, v203
	v_add3_u32 v203, s15, v203, v73
	v_xor_b32_e32 v204, 9, v63
	v_lshlrev_b32_e32 v204, 4, v204
	v_add3_u32 v204, s15, v204, v73
	v_xor_b32_e32 v205, 10, v63
	v_lshlrev_b32_e32 v205, 4, v205
	v_add3_u32 v205, s15, v205, v73
	v_xor_b32_e32 v206, 11, v63
	v_lshlrev_b32_e32 v206, 4, v206
	v_add3_u32 v206, s15, v206, v73
	v_xor_b32_e32 v207, 12, v63
	v_lshlrev_b32_e32 v207, 4, v207
	v_add3_u32 v207, s15, v207, v73
	v_xor_b32_e32 v208, 13, v63
	v_lshlrev_b32_e32 v208, 4, v208
	v_add3_u32 v208, s15, v208, v73
	v_xor_b32_e32 v209, 14, v63
	v_lshlrev_b32_e32 v209, 4, v209
	v_add3_u32 v209, s15, v209, v73
	v_xor_b32_e32 v210, 15, v63
	v_lshlrev_b32_e32 v210, 4, v210
	v_add3_u32 v210, s15, v210, v73
	v_mov_b32_e32 v134, v72
	v_or_b32_e32 v136, s12, v134
	v_ashrrev_i32_e32 v137, 31, v136
	v_lshlrev_b64 v[136:137], 11, v[136:137]
	v_or_b32_e32 v136, v136, v86
	v_lshl_add_u64 v[136:137], v[136:137], 2, s[60:61]
	global_load_dword v126, v[136:137], off
	v_or_b32_e32 v138, s54, v134
	v_ashrrev_i32_e32 v139, 31, v138
	v_lshlrev_b64 v[138:139], 11, v[138:139]
	v_or_b32_e32 v138, v138, v86
	v_lshl_add_u64 v[138:139], v[138:139], 2, s[60:61]
	global_load_dword v127, v[138:139], off
	v_or_b32_e32 v136, s55, v134
	v_ashrrev_i32_e32 v137, 31, v136
	v_lshlrev_b64 v[136:137], 11, v[136:137]
	v_or_b32_e32 v136, v136, v86
	v_lshl_add_u64 v[136:137], v[136:137], 2, s[60:61]
	global_load_dword v128, v[136:137], off
	v_or_b32_e32 v138, s68, v134
	v_ashrrev_i32_e32 v139, 31, v138
	v_lshlrev_b64 v[138:139], 11, v[138:139]
	v_or_b32_e32 v138, v138, v86
	v_lshl_add_u64 v[138:139], v[138:139], 2, s[60:61]
	global_load_dword v129, v[138:139], off
	v_or_b32_e32 v136, s13, v134
	v_ashrrev_i32_e32 v137, 31, v136
	v_lshlrev_b64 v[136:137], 11, v[136:137]
	v_or_b32_e32 v136, v136, v86
	v_lshl_add_u64 v[136:137], v[136:137], 2, s[60:61]
	global_load_dword v130, v[136:137], off
	v_or_b32_e32 v138, s77, v134
	v_ashrrev_i32_e32 v139, 31, v138
	v_lshlrev_b64 v[138:139], 11, v[138:139]
	v_or_b32_e32 v138, v138, v86
	v_lshl_add_u64 v[138:139], v[138:139], 2, s[60:61]
	global_load_dword v131, v[138:139], off
	v_or_b32_e32 v136, s80, v134
	v_ashrrev_i32_e32 v137, 31, v136
	v_lshlrev_b64 v[136:137], 11, v[136:137]
	v_or_b32_e32 v136, v136, v86
; __device__ __forceinline__ unsigned f2bf(float f) { unsigned u = __builtin_bit_cast(unsigned, f); return (u + 0x7fffu + ((u >> 16) & 1u)) >> 16; }
; __device__ __forceinline__ float gelu_tanh(float v) { const float z = 0.7978845608028654f * (v + 0.044715f * v * v * v); return v * (1.0f - 1.0f / (1.0f + __expf(2.0f * z))); }
; template <int PASS> __device__ __forceinline__ void ssm_phase(int j, LAS unsigned char* lds, int lane, int wave) { KARGS;
;     ...
;                     if (fq < 2) { const int l = 32 * half + 16 * lt + fr; const float rs = rsL[l]; const float* xp = X + (size_t)(64 * c + l) * D + 16 * g + 8 * fq;
;                         const f32x4 x0 = *(const f32x4*)xp * rs, x1 = *(const f32x4*)(xp + 4) * rs;
;     ...
;                         for (int r = 0; r < 4; ++r) { const int l = 32 * half + 16 * lt + 4 * fq + r; const size_t t = (size_t)(64 * c + l);
;                             const float v = y[r] + dd * X[t * D + ch] * rsL[l];
;                             GL[t * D + ch] = (bf16_t)f2bf(gelu_tanh(v)); }
	v_lshl_add_u64 v[136:137], v[136:137], 2, s[60:61]
	global_load_dword v132, v[136:137], off
	v_or_b32_e32 v138, s81, v134
	v_ashrrev_i32_e32 v139, 31, v138
	v_lshlrev_b64 v[138:139], 11, v[138:139]
	v_or_b32_e32 v138, v138, v86
	v_lshl_add_u64 v[138:139], v[138:139], 2, s[60:61]
	global_load_dword v133, v[138:139], off
	v_or_b32_e32 v134, 32, v72
	v_or_b32_e32 v136, s12, v134
	v_ashrrev_i32_e32 v137, 31, v136
	v_lshlrev_b64 v[136:137], 11, v[136:137]
	v_or_b32_e32 v136, v136, v86
	v_lshl_add_u64 v[136:137], v[136:137], 2, s[60:61]
	global_load_dword v236, v[136:137], off
	v_or_b32_e32 v138, s54, v134
	v_ashrrev_i32_e32 v139, 31, v138
	v_lshlrev_b64 v[138:139], 11, v[138:139]
	v_or_b32_e32 v138, v138, v86
	v_lshl_add_u64 v[138:139], v[138:139], 2, s[60:61]
	global_load_dword v237, v[138:139], off
	v_or_b32_e32 v136, s55, v134
	v_ashrrev_i32_e32 v137, 31, v136
	v_lshlrev_b64 v[136:137], 11, v[136:137]
	v_or_b32_e32 v136, v136, v86
	v_lshl_add_u64 v[136:137], v[136:137], 2, s[60:61]
	global_load_dword v238, v[136:137], off
	v_or_b32_e32 v138, s68, v134
	v_ashrrev_i32_e32 v139, 31, v138
	v_lshlrev_b64 v[138:139], 11, v[138:139]
	v_or_b32_e32 v138, v138, v86
	v_lshl_add_u64 v[138:139], v[138:139], 2, s[60:61]
	global_load_dword v239, v[138:139], off
	v_or_b32_e32 v136, s13, v134
	v_ashrrev_i32_e32 v137, 31, v136
	v_lshlrev_b64 v[136:137], 11, v[136:137]
	v_or_b32_e32 v136, v136, v86
	v_lshl_add_u64 v[136:137], v[136:137], 2, s[60:61]
	global_load_dword v240, v[136:137], off
	v_or_b32_e32 v138, s77, v134
	v_ashrrev_i32_e32 v139, 31, v138
	v_lshlrev_b64 v[138:139], 11, v[138:139]
	v_or_b32_e32 v138, v138, v86
	v_lshl_add_u64 v[138:139], v[138:139], 2, s[60:61]
	global_load_dword v241, v[138:139], off
	v_or_b32_e32 v136, s80, v134
	v_ashrrev_i32_e32 v137, 31, v136
	v_lshlrev_b64 v[136:137], 11, v[136:137]
	v_or_b32_e32 v136, v136, v86
	v_lshl_add_u64 v[136:137], v[136:137], 2, s[60:61]
	global_load_dword v242, v[136:137], off
	v_or_b32_e32 v138, s81, v134
	v_ashrrev_i32_e32 v139, 31, v138
	v_lshlrev_b64 v[138:139], 11, v[138:139]
	v_or_b32_e32 v138, v138, v86
	v_lshl_add_u64 v[138:139], v[138:139], 2, s[60:61]
	global_load_dword v243, v[138:139], off
	s_and_saveexec_b64 s[100:101], s[8:9]
	v_mov_b32_e32 v188, v62
	v_or_b32_e32 v188, s12, v188
	v_ashrrev_i32_e32 v189, 31, v188
	v_lshlrev_b64 v[188:189], 13, v[188:189]
	v_lshl_add_u64 v[188:189], v[88:89], 0, v[188:189]
	global_load_dwordx4 v[156:159], v[188:189], off
	global_load_dwordx4 v[160:163], v[188:189], off offset:16
	v_mov_b32_e32 v190, v62
	v_or_b32_e32 v190, s13, v190
	v_ashrrev_i32_e32 v191, 31, v190
	v_lshlrev_b64 v[190:191], 13, v[190:191]
	v_lshl_add_u64 v[190:191], v[88:89], 0, v[190:191]
	global_load_dwordx4 v[164:167], v[190:191], off
	global_load_dwordx4 v[168:171], v[190:191], off offset:16
	v_or_b32_e32 v188, 32, v62
	v_or_b32_e32 v188, s12, v188
	v_ashrrev_i32_e32 v189, 31, v188
	v_lshlrev_b64 v[188:189], 13, v[188:189]
	v_lshl_add_u64 v[188:189], v[88:89], 0, v[188:189]
	global_load_dwordx4 v[172:175], v[188:189], off
	global_load_dwordx4 v[176:179], v[188:189], off offset:16
	v_or_b32_e32 v190, 32, v62
	v_or_b32_e32 v190, s13, v190
	v_ashrrev_i32_e32 v191, 31, v190
	v_lshlrev_b64 v[190:191], 13, v[190:191]
	v_lshl_add_u64 v[190:191], v[88:89], 0, v[190:191]
	global_load_dwordx4 v[180:183], v[190:191], off
	global_load_dwordx4 v[184:187], v[190:191], off offset:16
	s_mov_b64 exec, s[100:101]
	s_cmp_eq_u32 s36, 0
	s_cbranch_scc1 .Lssm3_ct_nofl
	global_store_short_d16_hi v246, v212, s[64:65]
	global_store_short_d16_hi v247, v213, s[64:65]
	global_store_short_d16_hi v248, v214, s[64:65]
	global_store_short_d16_hi v249, v215, s[64:65]
	global_store_short_d16_hi v250, v216, s[64:65]
	global_store_short_d16_hi v251, v217, s[64:65]
	global_store_short_d16_hi v252, v244, s[64:65]
	global_store_short_d16_hi v253, v245, s[64:65]
	s_waitcnt vmcnt(8)
	s_branch .Lssm3_ct_cont

; #define CBAR() asm volatile("s_waitcnt lgkmcnt(0)" ::: "memory")
; template <int PASS> __device__ __forceinline__ void ssm_phase(int j, LAS unsigned char* lds, int lane, int wave) { KARGS;
;     ...
;             { const int t = 64 * c + lane; float ssq = 0.f;
; #pragma unroll
;               for (int q = 0; q < 8; ++q) { const f32x4 v = *(const f32x4*)(rsp + (size_t)t * 64 + 4 * q); ssq += (v[0] + v[1]) + (v[2] + v[3]); }
;               rsL[lane] = rsqrtf(ssq * (1.0f / D) + EPS); }
;             CBAR();
.Lssm3_ct_cont:
	v_add_f32_e32 v112, v52, v53
	v_add_f32_e32 v114, v54, v55
	v_mov_b32_e32 v108, v98
	v_mov_b32_e32 v109, v102
	v_mov_b32_e32 v102, v99
	v_pk_add_f32 v[98:99], v[108:109], v[102:103]
	v_mov_b32_e32 v102, v100
	v_mov_b32_e32 v103, v104
	v_mov_b32_e32 v104, v101
	v_pk_add_f32 v[100:101], v[102:103], v[104:105]
	s_nop 0
	v_pk_add_f32 v[98:99], v[98:99], v[100:101]
	s_nop 0
	v_add_f32_e32 v97, 0, v98
	v_add_f32_e32 v108, v97, v99
	v_mov_b32_e32 v98, v57
	v_mov_b32_e32 v99, v58
	v_mov_b32_e32 v57, v59
	v_pk_add_f32 v[56:57], v[98:99], v[56:57]
	s_nop 0
	v_pk_add_f32 v[110:111], v[56:57], v[56:57] op_sel:[0,1] op_sel_hi:[1,0]
	v_mov_b64_e32 v[52:53], v[140:141]
	v_mov_b64_e32 v[54:55], v[142:143]
	v_mov_b64_e32 v[56:57], v[144:145]
	v_mov_b64_e32 v[58:59], v[146:147]
	v_mov_b64_e32 v[98:99], v[148:149]
	v_mov_b64_e32 v[100:101], v[150:151]
	v_mov_b64_e32 v[102:103], v[152:153]
	v_mov_b64_e32 v[104:105], v[154:155]
	v_add_f32_e32 v56, v56, v57
	v_add_f32_e32 v58, v58, v59
	v_mov_b32_e32 v109, v102
	v_mov_b32_e32 v111, v103
	v_mov_b32_e32 v113, v104
	v_mov_b32_e32 v115, v105
	v_pk_add_f32 v[102:103], v[108:109], v[110:111]
	v_pk_add_f32 v[104:105], v[112:113], v[114:115]
	v_mov_b32_e32 v57, v54
	v_pk_add_f32 v[102:103], v[102:103], v[104:105]
	v_mov_b32_e32 v104, v99
	v_mov_b32_e32 v105, v100
	v_mov_b32_e32 v99, v101
	v_pk_add_f32 v[98:99], v[104:105], v[98:99]
	v_pk_add_f32 v[102:103], v[102:103], v[102:103] op_sel:[0,1] op_sel_hi:[1,0]
	v_pk_add_f32 v[98:99], v[98:99], v[98:99] op_sel:[0,1] op_sel_hi:[1,0]
	v_mov_b32_e32 v103, v52
	v_mov_b32_e32 v99, v53
	v_mov_b32_e32 v59, v55
	v_pk_add_f32 v[52:53], v[102:103], v[98:99]
	v_pk_add_f32 v[54:55], v[56:57], v[58:59]
	s_nop 0
	v_pk_add_f32 v[52:53], v[52:53], v[54:55]
	s_nop 0
	v_add_f32_e32 v52, v52, v53
	v_fmamk_f32 v52, v52, 0x3a000000, v223
	v_cmp_gt_f32_e32 vcc, s97, v52
	v_mul_f32_e32 v53, 0x4b800000, v52
	s_nop 0
	v_cndmask_b32_e32 v52, v52, v53, vcc
	v_rsq_f32_e32 v52, v52
	s_nop 0
	v_mul_f32_e32 v53, 0x45800000, v52
	v_cndmask_b32_e32 v52, v52, v53, vcc
	ds_write_b32 v81, v52 offset:16384
	s_waitcnt lgkmcnt(0)

; #define LAS __attribute__((address_space(3)))
; __device__ __forceinline__ unsigned pk2(float lo, float hi) { const f32x2 v = {lo, hi}; const bf16x2_t b = __builtin_convertvector(v, bf16x2_t); return __builtin_bit_cast(unsigned, b); }
; #define CBAR() asm volatile("s_waitcnt lgkmcnt(0)" ::: "memory")
; template <int PASS> __device__ __forceinline__ void ssm_phase(int j, LAS unsigned char* lds, int lane, int wave) { KARGS;
;     ...
;                     f32x4 dre[4], dim[4];
; #pragma unroll
;                     for (int pt = 0; pt < 4; ++pt) { const f32x4 z4 = {0.f, 0.f, 0.f, 0.f};
;                         dre[pt] = __builtin_amdgcn_mfma_f32_16x16x32_bf16(uf, bfr[pt], z4, 0, 0, 0); dim[pt] = __builtin_amdgcn_mfma_f32_16x16x32_bf16(uf, bfi[pt], z4, 0, 0, 0); }
;                     asm volatile("s_nop 15\n\ts_nop 15" : "+v"(dre[0]), "+v"(dre[1]), "+v"(dre[2]), "+v"(dre[3]), "+v"(dim[0]), "+v"(dim[1]), "+v"(dim[2]), "+v"(dim[3]));
; #pragma unroll
;                     for (int pt = 0; pt < 4; ++pt)
; #pragma unroll
;                         for (int r = 0; r < 4; ++r) *(LAS unsigned*)(buL + (16 * lt + 4 * fq + r) * 256 + 4 * (16 * pt + fr)) = pk2(dre[pt][r], dim[pt][r]);
;                 }
;                 CBAR();
; #pragma unroll 1
;                 for (int l8 = 0; l8 < 32; l8 += 8) {
;                     unsigned w[8];
; #pragma unroll
;                     for (int q = 0; q < 8; ++q) w[q] = *(const LAS unsigned*)(buL + (l8 + q) * 256 + 4 * p);
; #pragma unroll
;                     for (int q = 0; q < 8; ++q) {
;                         const float nr = abr * hr - abi * hi + bflo(w[q]), ni = abr * hi + abi * hr + bfhi(w[q]); hr = nr; hi = ni;
;                         if (PASS == 3) *(LAS unsigned*)(hL + (l8 + q) * 256 + ((((p >> 2) ^ ((l8 + q) & 15))) << 4) + (p & 3) * 4) = pk2(hr, hi);
.LBB0_347:
	s_or_b64 exec, exec, s[10:11]
	s_nop 0
	v_mfma_f32_16x16x32_bf16 v[56:59], v[52:55], v[12:15], 0
	s_xor_b64 s[10:11], s[4:5], -1
	s_mov_b32 s4, -8
	v_mfma_f32_16x16x32_bf16 v[98:101], v[52:55], v[8:11], 0
	v_mfma_f32_16x16x32_bf16 v[102:105], v[52:55], v[16:19], 0
	v_mfma_f32_16x16x32_bf16 v[106:109], v[52:55], v[4:7], 0
	v_mfma_f32_16x16x32_bf16 v[110:113], v[52:55], v[28:31], 0
	v_mfma_f32_16x16x32_bf16 v[114:117], v[52:55], v[24:27], 0
	v_mfma_f32_16x16x32_bf16 v[118:121], v[52:55], v[32:35], 0
	v_mfma_f32_16x16x32_bf16 v[52:55], v[52:55], v[20:23], 0
	s_nop 15
	s_nop 15
	s_nop 1
	v_cvt_pk_bf16_f32 v56, v56, v98
	s_nop 0
	v_cvt_pk_bf16_f32 v97, v102, v106
	v_add_u32_e32 v98, 0x3000, v96
	v_cvt_pk_bf16_f32 v57, v57, v99
	ds_write2_b32 v98, v56, v97 offset1:16
	v_cvt_pk_bf16_f32 v56, v103, v107
	v_cvt_pk_bf16_f32 v58, v58, v100
	ds_write2_b32 v98, v57, v56 offset0:64 offset1:80
	v_cvt_pk_bf16_f32 v56, v104, v108
	v_cvt_pk_bf16_f32 v59, v59, v101
	ds_write2_b32 v98, v58, v56 offset0:128 offset1:144
	v_cvt_pk_bf16_f32 v56, v105, v109
	ds_write2_b32 v98, v59, v56 offset0:192 offset1:208
	v_cvt_pk_bf16_f32 v56, v110, v114
	v_cvt_pk_bf16_f32 v52, v118, v52
	v_cvt_pk_bf16_f32 v57, v111, v115
	ds_write2_b32 v98, v56, v52 offset0:32 offset1:48
	v_cvt_pk_bf16_f32 v52, v119, v53
	v_cvt_pk_bf16_f32 v58, v112, v116
	ds_write2_b32 v98, v57, v52 offset0:96 offset1:112
	v_cvt_pk_bf16_f32 v52, v120, v54
	v_cvt_pk_bf16_f32 v59, v113, v117
	ds_write2_b32 v98, v58, v52 offset0:160 offset1:176
	v_cvt_pk_bf16_f32 v52, v121, v55
	ds_write2_b32 v98, v59, v52 offset0:224 offset1:240
	s_waitcnt lgkmcnt(0)
	ds_read2st64_b32 v[52:53], v211 offset0:0 offset1:1
	ds_read2st64_b32 v[54:55], v211 offset0:2 offset1:3
	ds_read2st64_b32 v[56:57], v211 offset0:4 offset1:5
	ds_read2st64_b32 v[58:59], v211 offset0:6 offset1:7
	s_waitcnt lgkmcnt(0)
	ds_read2st64_b32 v[98:99], v211 offset0:8 offset1:9
	ds_read2st64_b32 v[100:101], v211 offset0:10 offset1:11
	ds_read2st64_b32 v[102:103], v211 offset0:12 offset1:13
	ds_read2st64_b32 v[104:105], v211 offset0:14 offset1:15
	v_mul_f32_e32 v106, v84, v0
	v_mul_f32_e32 v107, v85, v1
	v_lshlrev_b32_e32 v108, 16, v52
	v_and_b32_e32 v109, 0xffff0000, v52
	v_fma_f32 v0, v2, v0, -v107
	v_fma_f32 v1, v3, v1, v106
	v_add_f32_e32 v0, v0, v108
	v_add_f32_e32 v1, v1, v109
	v_cvt_pk_bf16_f32 v110, v0, v1
	ds_write_b32 v195, v110
	v_mul_f32_e32 v111, v84, v0
	v_mul_f32_e32 v112, v85, v1
	v_lshlrev_b32_e32 v113, 16, v53
	v_and_b32_e32 v114, 0xffff0000, v53
	v_fma_f32 v0, v2, v0, -v112
	v_fma_f32 v1, v3, v1, v111
	v_add_f32_e32 v0, v0, v113
	v_add_f32_e32 v1, v1, v114
	v_cvt_pk_bf16_f32 v115, v0, v1
	ds_write_b32 v196, v115 offset:256
	v_mul_f32_e32 v106, v84, v0
	v_mul_f32_e32 v107, v85, v1
	v_lshlrev_b32_e32 v108, 16, v54
	v_and_b32_e32 v109, 0xffff0000, v54
	v_fma_f32 v0, v2, v0, -v107
	v_fma_f32 v1, v3, v1, v106
	v_add_f32_e32 v0, v0, v108
	v_add_f32_e32 v1, v1, v109
	v_cvt_pk_bf16_f32 v110, v0, v1
	ds_write_b32 v197, v110 offset:512
	v_mul_f32_e32 v111, v84, v0
	v_mul_f32_e32 v112, v85, v1
	v_lshlrev_b32_e32 v113, 16, v55
	v_and_b32_e32 v114, 0xffff0000, v55
	v_fma_f32 v0, v2, v0, -v112
	v_fma_f32 v1, v3, v1, v111
	v_add_f32_e32 v0, v0, v113
	v_add_f32_e32 v1, v1, v114
	v_cvt_pk_bf16_f32 v115, v0, v1
	ds_write_b32 v198, v115 offset:768
	v_mul_f32_e32 v106, v84, v0
	v_mul_f32_e32 v107, v85, v1
	v_lshlrev_b32_e32 v108, 16, v56
	v_and_b32_e32 v109, 0xffff0000, v56
	v_fma_f32 v0, v2, v0, -v107
	v_fma_f32 v1, v3, v1, v106
	v_add_f32_e32 v0, v0, v108
	v_add_f32_e32 v1, v1, v109
	v_cvt_pk_bf16_f32 v110, v0, v1
	ds_write_b32 v199, v110 offset:1024
	v_mul_f32_e32 v111, v84, v0
	v_mul_f32_e32 v112, v85, v1
	v_lshlrev_b32_e32 v113, 16, v57
	v_and_b32_e32 v114, 0xffff0000, v57
	v_fma_f32 v0, v2, v0, -v112
	v_fma_f32 v1, v3, v1, v111
	v_add_f32_e32 v0, v0, v113
	v_add_f32_e32 v1, v1, v114
	v_cvt_pk_bf16_f32 v115, v0, v1
	ds_write_b32 v200, v115 offset:1280
	v_mul_f32_e32 v106, v84, v0
	v_mul_f32_e32 v107, v85, v1
	v_lshlrev_b32_e32 v108, 16, v58
	v_and_b32_e32 v109, 0xffff0000, v58
	v_fma_f32 v0, v2, v0, -v107
	v_fma_f32 v1, v3, v1, v106
	v_add_f32_e32 v0, v0, v108
	v_add_f32_e32 v1, v1, v109
	v_cvt_pk_bf16_f32 v110, v0, v1
	ds_write_b32 v201, v110 offset:1536
	v_mul_f32_e32 v111, v84, v0
	v_mul_f32_e32 v112, v85, v1
	v_lshlrev_b32_e32 v113, 16, v59
	v_and_b32_e32 v114, 0xffff0000, v59
	v_fma_f32 v0, v2, v0, -v112
	v_fma_f32 v1, v3, v1, v111
	v_add_f32_e32 v0, v0, v113
	v_add_f32_e32 v1, v1, v114
	v_cvt_pk_bf16_f32 v115, v0, v1
	ds_write_b32 v202, v115 offset:1792
	s_waitcnt lgkmcnt(8)
; #define LAS __attribute__((address_space(3)))
; __device__ __forceinline__ unsigned pk2(float lo, float hi) { const f32x2 v = {lo, hi}; const bf16x2_t b = __builtin_convertvector(v, bf16x2_t); return __builtin_bit_cast(unsigned, b); }
; template <int PASS> __device__ __forceinline__ void ssm_phase(int j, LAS unsigned char* lds, int lane, int wave) { KARGS;
;     ...
;                 for (int l8 = 0; l8 < 32; l8 += 8) {
;                     unsigned w[8];
; #pragma unroll
;                     for (int q = 0; q < 8; ++q) w[q] = *(const LAS unsigned*)(buL + (l8 + q) * 256 + 4 * p);
; #pragma unroll
;                     for (int q = 0; q < 8; ++q) {
;                         const float nr = abr * hr - abi * hi + bflo(w[q]), ni = abr * hi + abi * hr + bfhi(w[q]); hr = nr; hi = ni;
;                         if (PASS == 3) *(LAS unsigned*)(hL + (l8 + q) * 256 + ((((p >> 2) ^ ((l8 + q) & 15))) << 4) + (p & 3) * 4) = pk2(hr, hi);
;                     }
	ds_read2st64_b32 v[52:53], v211 offset0:16 offset1:17
	ds_read2st64_b32 v[54:55], v211 offset0:18 offset1:19
	ds_read2st64_b32 v[56:57], v211 offset0:20 offset1:21
	ds_read2st64_b32 v[58:59], v211 offset0:22 offset1:23
	v_mul_f32_e32 v106, v84, v0
	v_mul_f32_e32 v107, v85, v1
	v_lshlrev_b32_e32 v108, 16, v98
	v_and_b32_e32 v109, 0xffff0000, v98
	v_fma_f32 v0, v2, v0, -v107
	v_fma_f32 v1, v3, v1, v106
	v_add_f32_e32 v0, v0, v108
	v_add_f32_e32 v1, v1, v109
	v_cvt_pk_bf16_f32 v110, v0, v1
	ds_write_b32 v203, v110 offset:2048
	v_mul_f32_e32 v111, v84, v0
	v_mul_f32_e32 v112, v85, v1
	v_lshlrev_b32_e32 v113, 16, v99
	v_and_b32_e32 v114, 0xffff0000, v99
	v_fma_f32 v0, v2, v0, -v112
	v_fma_f32 v1, v3, v1, v111
	v_add_f32_e32 v0, v0, v113
	v_add_f32_e32 v1, v1, v114
	v_cvt_pk_bf16_f32 v115, v0, v1
	ds_write_b32 v204, v115 offset:2304
	v_mul_f32_e32 v106, v84, v0
	v_mul_f32_e32 v107, v85, v1
	v_lshlrev_b32_e32 v108, 16, v100
	v_and_b32_e32 v109, 0xffff0000, v100
	v_fma_f32 v0, v2, v0, -v107
	v_fma_f32 v1, v3, v1, v106
	v_add_f32_e32 v0, v0, v108
	v_add_f32_e32 v1, v1, v109
	v_cvt_pk_bf16_f32 v110, v0, v1
	ds_write_b32 v205, v110 offset:2560
	v_mul_f32_e32 v111, v84, v0
	v_mul_f32_e32 v112, v85, v1
	v_lshlrev_b32_e32 v113, 16, v101
	v_and_b32_e32 v114, 0xffff0000, v101
	v_fma_f32 v0, v2, v0, -v112
	v_fma_f32 v1, v3, v1, v111
	v_add_f32_e32 v0, v0, v113
	v_add_f32_e32 v1, v1, v114
	v_cvt_pk_bf16_f32 v115, v0, v1
	ds_write_b32 v206, v115 offset:2816
	v_mul_f32_e32 v106, v84, v0
	v_mul_f32_e32 v107, v85, v1
	v_lshlrev_b32_e32 v108, 16, v102
	v_and_b32_e32 v109, 0xffff0000, v102
	v_fma_f32 v0, v2, v0, -v107
	v_fma_f32 v1, v3, v1, v106
	v_add_f32_e32 v0, v0, v108
	v_add_f32_e32 v1, v1, v109
	v_cvt_pk_bf16_f32 v110, v0, v1
	ds_write_b32 v207, v110 offset:3072
	v_mul_f32_e32 v111, v84, v0
	v_mul_f32_e32 v112, v85, v1
	v_lshlrev_b32_e32 v113, 16, v103
	v_and_b32_e32 v114, 0xffff0000, v103
	v_fma_f32 v0, v2, v0, -v112
	v_fma_f32 v1, v3, v1, v111
	v_add_f32_e32 v0, v0, v113
	v_add_f32_e32 v1, v1, v114
	v_cvt_pk_bf16_f32 v115, v0, v1
	ds_write_b32 v208, v115 offset:3328
	v_mul_f32_e32 v106, v84, v0
	v_mul_f32_e32 v107, v85, v1
	v_lshlrev_b32_e32 v108, 16, v104
	v_and_b32_e32 v109, 0xffff0000, v104
	v_fma_f32 v0, v2, v0, -v107
	v_fma_f32 v1, v3, v1, v106
	v_add_f32_e32 v0, v0, v108
	v_add_f32_e32 v1, v1, v109
	v_cvt_pk_bf16_f32 v110, v0, v1
	ds_write_b32 v209, v110 offset:3584
	v_mul_f32_e32 v111, v84, v0
	v_mul_f32_e32 v112, v85, v1
	v_lshlrev_b32_e32 v113, 16, v105
	v_and_b32_e32 v114, 0xffff0000, v105
	v_fma_f32 v0, v2, v0, -v112
	v_fma_f32 v1, v3, v1, v111
	v_add_f32_e32 v0, v0, v113
	v_add_f32_e32 v1, v1, v114
	v_cvt_pk_bf16_f32 v115, v0, v1
	ds_write_b32 v210, v115 offset:3840
	s_waitcnt lgkmcnt(8)
	ds_read2st64_b32 v[98:99], v211 offset0:24 offset1:25
	ds_read2st64_b32 v[100:101], v211 offset0:26 offset1:27
	ds_read2st64_b32 v[102:103], v211 offset0:28 offset1:29
	ds_read2st64_b32 v[104:105], v211 offset0:30 offset1:31
	v_mul_f32_e32 v106, v84, v0
	v_mul_f32_e32 v107, v85, v1
	v_lshlrev_b32_e32 v108, 16, v52
	v_and_b32_e32 v109, 0xffff0000, v52
	v_fma_f32 v0, v2, v0, -v107
	v_fma_f32 v1, v3, v1, v106
	v_add_f32_e32 v0, v0, v108
	v_add_f32_e32 v1, v1, v109
	v_cvt_pk_bf16_f32 v110, v0, v1
	ds_write_b32 v195, v110 offset:4096
	v_mul_f32_e32 v111, v84, v0
	v_mul_f32_e32 v112, v85, v1
	v_lshlrev_b32_e32 v113, 16, v53
	v_and_b32_e32 v114, 0xffff0000, v53
	v_fma_f32 v0, v2, v0, -v112
	v_fma_f32 v1, v3, v1, v111
	v_add_f32_e32 v0, v0, v113
	v_add_f32_e32 v1, v1, v114
	v_cvt_pk_bf16_f32 v115, v0, v1
	ds_write_b32 v196, v115 offset:4352
	v_mul_f32_e32 v106, v84, v0
	v_mul_f32_e32 v107, v85, v1
	v_lshlrev_b32_e32 v108, 16, v54
	v_and_b32_e32 v109, 0xffff0000, v54
	v_fma_f32 v0, v2, v0, -v107
	v_fma_f32 v1, v3, v1, v106
	v_add_f32_e32 v0, v0, v108
	v_add_f32_e32 v1, v1, v109
	v_cvt_pk_bf16_f32 v110, v0, v1
	ds_write_b32 v197, v110 offset:4608
	v_mul_f32_e32 v111, v84, v0
	v_mul_f32_e32 v112, v85, v1
	v_lshlrev_b32_e32 v113, 16, v55
	v_and_b32_e32 v114, 0xffff0000, v55
	v_fma_f32 v0, v2, v0, -v112
	v_fma_f32 v1, v3, v1, v111
	v_add_f32_e32 v0, v0, v113
	v_add_f32_e32 v1, v1, v114
	v_cvt_pk_bf16_f32 v115, v0, v1
	ds_write_b32 v198, v115 offset:4864
	v_mul_f32_e32 v106, v84, v0
	v_mul_f32_e32 v107, v85, v1
	v_lshlrev_b32_e32 v108, 16, v56
	v_and_b32_e32 v109, 0xffff0000, v56
	v_fma_f32 v0, v2, v0, -v107
	v_fma_f32 v1, v3, v1, v106
	v_add_f32_e32 v0, v0, v108
	v_add_f32_e32 v1, v1, v109
	v_cvt_pk_bf16_f32 v110, v0, v1
	ds_write_b32 v199, v110 offset:5120
	v_mul_f32_e32 v111, v84, v0
	v_mul_f32_e32 v112, v85, v1
	v_lshlrev_b32_e32 v113, 16, v57
	v_and_b32_e32 v114, 0xffff0000, v57
	v_fma_f32 v0, v2, v0, -v112
	v_fma_f32 v1, v3, v1, v111
	v_add_f32_e32 v0, v0, v113
	v_add_f32_e32 v1, v1, v114
	v_cvt_pk_bf16_f32 v115, v0, v1
	ds_write_b32 v200, v115 offset:5376
	v_mul_f32_e32 v106, v84, v0
	v_mul_f32_e32 v107, v85, v1
	v_lshlrev_b32_e32 v108, 16, v58
	v_and_b32_e32 v109, 0xffff0000, v58
	v_fma_f32 v0, v2, v0, -v107
	v_fma_f32 v1, v3, v1, v106
	v_add_f32_e32 v0, v0, v108
	v_add_f32_e32 v1, v1, v109
	v_cvt_pk_bf16_f32 v110, v0, v1
	ds_write_b32 v201, v110 offset:5632
	v_mul_f32_e32 v111, v84, v0
	v_mul_f32_e32 v112, v85, v1
	v_lshlrev_b32_e32 v113, 16, v59
	v_and_b32_e32 v114, 0xffff0000, v59
	v_fma_f32 v0, v2, v0, -v112
	v_fma_f32 v1, v3, v1, v111
	v_add_f32_e32 v0, v0, v113
	v_add_f32_e32 v1, v1, v114
	v_cvt_pk_bf16_f32 v115, v0, v1
	ds_write_b32 v202, v115 offset:5888
	s_waitcnt lgkmcnt(8)
; #define LAS __attribute__((address_space(3)))
; __device__ __forceinline__ unsigned f2bf(float f) { unsigned u = __builtin_bit_cast(unsigned, f); return (u + 0x7fffu + ((u >> 16) & 1u)) >> 16; }
; __device__ __forceinline__ unsigned pk2(float lo, float hi) { const f32x2 v = {lo, hi}; const bf16x2_t b = __builtin_convertvector(v, bf16x2_t); return __builtin_bit_cast(unsigned, b); }
; __device__ __forceinline__ float gelu_tanh(float v) { const float z = 0.7978845608028654f * (v + 0.044715f * v * v * v); return v * (1.0f - 1.0f / (1.0f + __expf(2.0f * z))); }
; #define CBAR() asm volatile("s_waitcnt lgkmcnt(0)" ::: "memory")
; template <int PASS> __device__ __forceinline__ void ssm_phase(int j, LAS unsigned char* lds, int lane, int wave) { KARGS;
;     ...
;                     for (int q = 0; q < 8; ++q) {
;                         const float nr = abr * hr - abi * hi + bflo(w[q]), ni = abr * hi + abi * hr + bfhi(w[q]); hr = nr; hi = ni;
;                         if (PASS == 3) *(LAS unsigned*)(hL + (l8 + q) * 256 + ((((p >> 2) ^ ((l8 + q) & 15))) << 4) + (p & 3) * 4) = pk2(hr, hi);
;                     }
;                 }
;                 CBAR();
;                 if (PASS == 3) {
; #pragma unroll
;                     for (int lt = 0; lt < 2; ++lt) {
;                         f32x4 y = {0.f, 0.f, 0.f, 0.f};
; #pragma unroll
;                         for (int ks = 0; ks < 4; ++ks) { const bf16x8 hf = *(const LAS bf16x8*)(hL + (16 * lt + fr) * 256 + (((4 * ks + fq) ^ fr) << 4)); y = __builtin_amdgcn_mfma_f32_16x16x32_bf16(hf, cf[ks], y, 0, 0, 0); }
;                         asm volatile("s_nop 15\n\ts_nop 15" : "+v"(y));
;                         const int ch = 16 * g + fr;
; #pragma unroll
;                         for (int r = 0; r < 4; ++r) { const int l = 32 * half + 16 * lt + 4 * fq + r; const size_t t = (size_t)(64 * c + l);
;                             const float v = y[r] + dd * X[t * D + ch] * rsL[l];
;                             GL[t * D + ch] = (bf16_t)f2bf(gelu_tanh(v)); }
	v_mul_f32_e32 v106, v84, v0
	v_mul_f32_e32 v107, v85, v1
	v_lshlrev_b32_e32 v108, 16, v98
	v_and_b32_e32 v109, 0xffff0000, v98
	v_fma_f32 v0, v2, v0, -v107
	v_fma_f32 v1, v3, v1, v106
	v_add_f32_e32 v0, v0, v108
	v_add_f32_e32 v1, v1, v109
	v_cvt_pk_bf16_f32 v110, v0, v1
	ds_write_b32 v203, v110 offset:6144
	v_mul_f32_e32 v111, v84, v0
	v_mul_f32_e32 v112, v85, v1
	v_lshlrev_b32_e32 v113, 16, v99
	v_and_b32_e32 v114, 0xffff0000, v99
	v_fma_f32 v0, v2, v0, -v112
	v_fma_f32 v1, v3, v1, v111
	v_add_f32_e32 v0, v0, v113
	v_add_f32_e32 v1, v1, v114
	v_cvt_pk_bf16_f32 v115, v0, v1
	ds_write_b32 v204, v115 offset:6400
	v_mul_f32_e32 v106, v84, v0
	v_mul_f32_e32 v107, v85, v1
	v_lshlrev_b32_e32 v108, 16, v100
	v_and_b32_e32 v109, 0xffff0000, v100
	v_fma_f32 v0, v2, v0, -v107
	v_fma_f32 v1, v3, v1, v106
	v_add_f32_e32 v0, v0, v108
	v_add_f32_e32 v1, v1, v109
	v_cvt_pk_bf16_f32 v110, v0, v1
	ds_write_b32 v205, v110 offset:6656
	v_mul_f32_e32 v111, v84, v0
	v_mul_f32_e32 v112, v85, v1
	v_lshlrev_b32_e32 v113, 16, v101
	v_and_b32_e32 v114, 0xffff0000, v101
	v_fma_f32 v0, v2, v0, -v112
	v_fma_f32 v1, v3, v1, v111
	v_add_f32_e32 v0, v0, v113
	v_add_f32_e32 v1, v1, v114
	v_cvt_pk_bf16_f32 v115, v0, v1
	ds_write_b32 v206, v115 offset:6912
	v_mul_f32_e32 v106, v84, v0
	v_mul_f32_e32 v107, v85, v1
	v_lshlrev_b32_e32 v108, 16, v102
	v_and_b32_e32 v109, 0xffff0000, v102
	v_fma_f32 v0, v2, v0, -v107
	v_fma_f32 v1, v3, v1, v106
	v_add_f32_e32 v0, v0, v108
	v_add_f32_e32 v1, v1, v109
	v_cvt_pk_bf16_f32 v110, v0, v1
	ds_write_b32 v207, v110 offset:7168
	v_mul_f32_e32 v111, v84, v0
	v_mul_f32_e32 v112, v85, v1
	v_lshlrev_b32_e32 v113, 16, v103
	v_and_b32_e32 v114, 0xffff0000, v103
	v_fma_f32 v0, v2, v0, -v112
	v_fma_f32 v1, v3, v1, v111
	v_add_f32_e32 v0, v0, v113
	v_add_f32_e32 v1, v1, v114
	v_cvt_pk_bf16_f32 v115, v0, v1
	ds_write_b32 v208, v115 offset:7424
	v_mul_f32_e32 v106, v84, v0
	v_mul_f32_e32 v107, v85, v1
	v_lshlrev_b32_e32 v108, 16, v104
	v_and_b32_e32 v109, 0xffff0000, v104
	v_fma_f32 v0, v2, v0, -v107
	v_fma_f32 v1, v3, v1, v106
	v_add_f32_e32 v0, v0, v108
	v_add_f32_e32 v1, v1, v109
	v_cvt_pk_bf16_f32 v110, v0, v1
	ds_write_b32 v209, v110 offset:7680
	v_mul_f32_e32 v111, v84, v0
	v_mul_f32_e32 v112, v85, v1
	v_lshlrev_b32_e32 v113, 16, v105
	v_and_b32_e32 v114, 0xffff0000, v105
	v_fma_f32 v0, v2, v0, -v112
	v_fma_f32 v1, v3, v1, v111
	v_add_f32_e32 v0, v0, v113
	v_add_f32_e32 v1, v1, v114
	v_cvt_pk_bf16_f32 v115, v0, v1
	ds_write_b32 v210, v115 offset:7936
	s_waitcnt lgkmcnt(0)
	ds_read_b128 v[52:55], v87
	ds_read_b128 v[56:59], v92
	v_or_b32_e32 v97, s70, v72
	v_lshl_add_u32 v98, v97, 2, s18
	s_mov_b32 s70, 32
	s_waitcnt lgkmcnt(1)
	v_mfma_f32_16x16x32_bf16 v[52:55], v[52:55], v[36:39], 0
	s_waitcnt lgkmcnt(0)
	v_mfma_f32_16x16x32_bf16 v[52:55], v[56:59], v[40:43], v[52:55]
	ds_read_b128 v[56:59], v93
	s_waitcnt lgkmcnt(0)
	v_mfma_f32_16x16x32_bf16 v[52:55], v[56:59], v[44:47], v[52:55]
	ds_read_b128 v[56:59], v94
	s_waitcnt lgkmcnt(0)
	v_mfma_f32_16x16x32_bf16 v[52:55], v[56:59], v[48:51], v[52:55]
	v_or_b32_e32 v56, s12, v97
	v_ashrrev_i32_e32 v57, 31, v56
	v_lshlrev_b64 v[100:101], 11, v[56:57]
	v_or_b32_e32 v100, v100, v86
	v_lshl_add_u64 v[56:57], v[100:101], 2, s[60:61]
	s_nop 15
	s_nop 15
	v_lshlrev_b32_e32 v246, 1, v100
	v_lshl_add_u64 v[100:101], v[100:101], 1, s[64:65]
	v_mul_f32_e32 v99, v83, v126
	ds_read_b128 v[56:59], v98 offset:16384
	s_waitcnt lgkmcnt(0)
	v_fma_f32 v52, v99, v56, v52
	v_mul_f32_e32 v56, 0x3d372713, v52
	v_mul_f32_e32 v56, v52, v56
	v_fma_f32 v56, v52, v56, v52
	v_mul_f32_e32 v56, 0x3f4c422a, v56
	v_add_f32_e32 v56, v56, v56
	v_mul_f32_e32 v56, 0x3fb8aa3b, v56
	v_exp_f32_e32 v56, v56
	s_nop 0
	v_add_f32_e32 v56, 1.0, v56
	v_div_scale_f32 v99, s[4:5], v56, v56, 1.0
	v_rcp_f32_e32 v102, v99
	s_nop 0
	v_fma_f32 v103, -v99, v102, 1.0
	v_fmac_f32_e32 v102, v103, v102
	v_div_scale_f32 v103, vcc, 1.0, v56, 1.0
	v_mul_f32_e32 v104, v103, v102
	v_fma_f32 v105, -v99, v104, v103
	v_fmac_f32_e32 v104, v105, v102
	v_fma_f32 v99, -v99, v104, v103
	v_div_fmas_f32 v99, v99, v102, v104
	v_div_fixup_f32 v56, v99, v56, 1.0
	v_sub_f32_e32 v56, 1.0, v56
	v_mul_f32_e32 v52, v52, v56
	v_bfe_u32 v56, v52, 16, 1
	v_add3_u32 v52, v52, v56, s75
	v_mov_b32_e32 v212, v52
	v_or_b32_e32 v100, s54, v97
	v_ashrrev_i32_e32 v101, 31, v100
	v_lshlrev_b64 v[100:101], 11, v[100:101]
	v_or_b32_e32 v100, v100, v86
	v_lshl_add_u64 v[102:103], v[100:101], 2, s[60:61]
	v_mul_f32_e32 v52, v83, v127
	v_fma_f32 v52, v52, v57, v53
	v_mul_f32_e32 v53, 0x3d372713, v52
	v_mul_f32_e32 v53, v52, v53
	v_fma_f32 v53, v52, v53, v52
	v_mul_f32_e32 v53, 0x3f4c422a, v53
	v_add_f32_e32 v53, v53, v53
	v_mul_f32_e32 v53, 0x3fb8aa3b, v53
	v_exp_f32_e32 v53, v53
	s_nop 0
	v_add_f32_e32 v53, 1.0, v53
	v_div_scale_f32 v56, s[4:5], v53, v53, 1.0
	v_rcp_f32_e32 v57, v56
	s_nop 0
	v_fma_f32 v99, -v56, v57, 1.0
	v_fmac_f32_e32 v57, v99, v57
	v_div_scale_f32 v99, vcc, 1.0, v53, 1.0
	v_mul_f32_e32 v102, v99, v57
	v_fma_f32 v103, -v56, v102, v99
	v_fmac_f32_e32 v102, v103, v57
	v_fma_f32 v56, -v56, v102, v99
	v_div_fmas_f32 v56, v56, v57, v102
	v_div_fixup_f32 v53, v56, v53, 1.0
	v_sub_f32_e32 v53, 1.0, v53
	v_mul_f32_e32 v52, v52, v53
	v_bfe_u32 v53, v52, 16, 1
	v_add3_u32 v56, v52, v53, s75
	v_lshlrev_b32_e32 v247, 1, v100
	v_lshl_add_u64 v[52:53], v[100:101], 1, s[64:65]
	v_mov_b32_e32 v213, v56
	v_or_b32_e32 v52, s55, v97
	v_ashrrev_i32_e32 v53, 31, v52
	v_lshlrev_b64 v[52:53], 11, v[52:53]
	v_or_b32_e32 v52, v52, v86
	v_lshl_add_u64 v[56:57], v[52:53], 2, s[60:61]
	v_lshlrev_b32_e32 v248, 1, v52
	v_lshl_add_u64 v[52:53], v[52:53], 1, s[64:65]
	v_mul_f32_e32 v56, v83, v128
; #define LAS __attribute__((address_space(3)))
; __device__ __forceinline__ unsigned f2bf(float f) { unsigned u = __builtin_bit_cast(unsigned, f); return (u + 0x7fffu + ((u >> 16) & 1u)) >> 16; }
; __device__ __forceinline__ float gelu_tanh(float v) { const float z = 0.7978845608028654f * (v + 0.044715f * v * v * v); return v * (1.0f - 1.0f / (1.0f + __expf(2.0f * z))); }
; template <int PASS> __device__ __forceinline__ void ssm_phase(int j, LAS unsigned char* lds, int lane, int wave) { KARGS;
;     ...
;                     for (int lt = 0; lt < 2; ++lt) {
;                         f32x4 y = {0.f, 0.f, 0.f, 0.f};
; #pragma unroll
;                         for (int ks = 0; ks < 4; ++ks) { const bf16x8 hf = *(const LAS bf16x8*)(hL + (16 * lt + fr) * 256 + (((4 * ks + fq) ^ fr) << 4)); y = __builtin_amdgcn_mfma_f32_16x16x32_bf16(hf, cf[ks], y, 0, 0, 0); }
;                         asm volatile("s_nop 15\n\ts_nop 15" : "+v"(y));
;                         const int ch = 16 * g + fr;
; #pragma unroll
;                         for (int r = 0; r < 4; ++r) { const int l = 32 * half + 16 * lt + 4 * fq + r; const size_t t = (size_t)(64 * c + l);
;                             const float v = y[r] + dd * X[t * D + ch] * rsL[l];
;                             GL[t * D + ch] = (bf16_t)f2bf(gelu_tanh(v)); }
	v_fma_f32 v54, v56, v58, v54
	v_mul_f32_e32 v56, 0x3d372713, v54
	v_mul_f32_e32 v56, v54, v56
	v_fma_f32 v56, v54, v56, v54
	v_mul_f32_e32 v56, 0x3f4c422a, v56
	v_add_f32_e32 v56, v56, v56
	v_mul_f32_e32 v56, 0x3fb8aa3b, v56
	v_exp_f32_e32 v56, v56
	s_nop 0
	v_add_f32_e32 v56, 1.0, v56
	v_div_scale_f32 v57, s[4:5], v56, v56, 1.0
	v_rcp_f32_e32 v58, v57
	s_nop 0
	v_fma_f32 v99, -v57, v58, 1.0
	v_fmac_f32_e32 v58, v99, v58
	v_div_scale_f32 v99, vcc, 1.0, v56, 1.0
	v_mul_f32_e32 v100, v99, v58
	v_fma_f32 v101, -v57, v100, v99
	v_fmac_f32_e32 v100, v101, v58
	v_fma_f32 v57, -v57, v100, v99
	v_div_fmas_f32 v57, v57, v58, v100
	v_div_fixup_f32 v56, v57, v56, 1.0
	v_sub_f32_e32 v56, 1.0, v56
	v_mul_f32_e32 v54, v54, v56
	v_bfe_u32 v56, v54, 16, 1
	v_add3_u32 v54, v54, v56, s75
	v_mov_b32_e32 v214, v54
	v_or_b32_e32 v52, s68, v97
	v_ashrrev_i32_e32 v53, 31, v52
	v_lshlrev_b64 v[52:53], 11, v[52:53]
	v_or_b32_e32 v52, v52, v86
	v_lshl_add_u64 v[56:57], v[52:53], 2, s[60:61]
	v_lshlrev_b32_e32 v249, 1, v52
	v_lshl_add_u64 v[52:53], v[52:53], 1, s[64:65]
	v_mul_f32_e32 v54, v83, v129
	v_fmac_f32_e32 v55, v54, v59
	v_mul_f32_e32 v54, 0x3d372713, v55
	v_mul_f32_e32 v54, v55, v54
	v_fma_f32 v54, v55, v54, v55
	v_mul_f32_e32 v54, 0x3f4c422a, v54
	v_add_f32_e32 v54, v54, v54
	v_mul_f32_e32 v54, 0x3fb8aa3b, v54
	v_exp_f32_e32 v54, v54
	s_nop 0
	v_add_f32_e32 v54, 1.0, v54
	v_div_scale_f32 v56, s[4:5], v54, v54, 1.0
	v_rcp_f32_e32 v57, v56
	s_nop 0
	v_fma_f32 v58, -v56, v57, 1.0
	v_fmac_f32_e32 v57, v58, v57
	v_div_scale_f32 v58, vcc, 1.0, v54, 1.0
	v_mul_f32_e32 v59, v58, v57
	v_fma_f32 v99, -v56, v59, v58
	v_fmac_f32_e32 v59, v99, v57
	v_fma_f32 v56, -v56, v59, v58
	v_div_fmas_f32 v56, v56, v57, v59
	v_div_fixup_f32 v54, v56, v54, 1.0
	v_sub_f32_e32 v54, 1.0, v54
	v_mul_f32_e32 v54, v55, v54
	v_bfe_u32 v55, v54, 16, 1
	v_add3_u32 v54, v54, v55, s75
	v_mov_b32_e32 v215, v54
	ds_read_b128 v[52:55], v87 offset:4096
	ds_read_b128 v[56:59], v92 offset:4096
	s_waitcnt lgkmcnt(1)
	v_mfma_f32_16x16x32_bf16 v[52:55], v[52:55], v[36:39], 0
	s_waitcnt lgkmcnt(0)
	v_mfma_f32_16x16x32_bf16 v[52:55], v[56:59], v[40:43], v[52:55]
	ds_read_b128 v[56:59], v93 offset:4096
	s_waitcnt lgkmcnt(0)
	v_mfma_f32_16x16x32_bf16 v[52:55], v[56:59], v[44:47], v[52:55]
	ds_read_b128 v[56:59], v94 offset:4096
	s_waitcnt lgkmcnt(0)
	v_mfma_f32_16x16x32_bf16 v[52:55], v[56:59], v[48:51], v[52:55]
	v_or_b32_e32 v56, s13, v97
	v_ashrrev_i32_e32 v57, 31, v56
	v_lshlrev_b64 v[100:101], 11, v[56:57]
	v_or_b32_e32 v100, v100, v86
	v_lshl_add_u64 v[56:57], v[100:101], 2, s[60:61]
	s_nop 15
	s_nop 15
	v_mul_f32_e32 v99, v83, v130
	ds_read_b128 v[56:59], v98 offset:16448
	s_waitcnt lgkmcnt(0)
; #define LAS __attribute__((address_space(3)))
; __device__ __forceinline__ unsigned f2bf(float f) { unsigned u = __builtin_bit_cast(unsigned, f); return (u + 0x7fffu + ((u >> 16) & 1u)) >> 16; }
; __device__ __forceinline__ float gelu_tanh(float v) { const float z = 0.7978845608028654f * (v + 0.044715f * v * v * v); return v * (1.0f - 1.0f / (1.0f + __expf(2.0f * z))); }
; #define CBAR() asm volatile("s_waitcnt lgkmcnt(0)" ::: "memory")
; template <int PASS> __device__ __forceinline__ void ssm_phase(int j, LAS unsigned char* lds, int lane, int wave) { KARGS;
;     ...
;             for (int half = 0; half < 2; ++half) {
;     ...
;                     for (int lt = 0; lt < 2; ++lt) {
;                         f32x4 y = {0.f, 0.f, 0.f, 0.f};
; #pragma unroll
;                         for (int ks = 0; ks < 4; ++ks) { const bf16x8 hf = *(const LAS bf16x8*)(hL + (16 * lt + fr) * 256 + (((4 * ks + fq) ^ fr) << 4)); y = __builtin_amdgcn_mfma_f32_16x16x32_bf16(hf, cf[ks], y, 0, 0, 0); }
;                         asm volatile("s_nop 15\n\ts_nop 15" : "+v"(y));
;                         const int ch = 16 * g + fr;
; #pragma unroll
;                         for (int r = 0; r < 4; ++r) { const int l = 32 * half + 16 * lt + 4 * fq + r; const size_t t = (size_t)(64 * c + l);
;                             const float v = y[r] + dd * X[t * D + ch] * rsL[l];
;                             GL[t * D + ch] = (bf16_t)f2bf(gelu_tanh(v)); }
;                     }
;                     CBAR();
	v_fma_f32 v52, v99, v56, v52
	v_mul_f32_e32 v56, 0x3d372713, v52
	v_mul_f32_e32 v56, v52, v56
	v_fma_f32 v56, v52, v56, v52
	v_mul_f32_e32 v56, 0x3f4c422a, v56
	v_add_f32_e32 v56, v56, v56
	v_mul_f32_e32 v56, 0x3fb8aa3b, v56
	v_exp_f32_e32 v56, v56
	s_nop 0
	v_add_f32_e32 v56, 1.0, v56
	v_div_scale_f32 v98, s[4:5], v56, v56, 1.0
	v_rcp_f32_e32 v99, v98
	s_nop 0
	v_fma_f32 v102, -v98, v99, 1.0
	v_fmac_f32_e32 v99, v102, v99
	v_div_scale_f32 v102, vcc, 1.0, v56, 1.0
	v_mul_f32_e32 v103, v102, v99
	v_fma_f32 v104, -v98, v103, v102
	v_fmac_f32_e32 v103, v104, v99
	v_fma_f32 v98, -v98, v103, v102
	v_div_fmas_f32 v98, v98, v99, v103
	v_div_fixup_f32 v56, v98, v56, 1.0
	v_sub_f32_e32 v56, 1.0, v56
	v_mul_f32_e32 v52, v52, v56
	v_bfe_u32 v56, v52, 16, 1
	v_add3_u32 v52, v52, v56, s75
	v_lshlrev_b32_e32 v250, 1, v100
	v_lshl_add_u64 v[98:99], v[100:101], 1, s[64:65]
	v_mov_b32_e32 v216, v52
	v_or_b32_e32 v98, s77, v97
	v_ashrrev_i32_e32 v99, 31, v98
	v_lshlrev_b64 v[98:99], 11, v[98:99]
	v_or_b32_e32 v98, v98, v86
	v_lshl_add_u64 v[100:101], v[98:99], 2, s[60:61]
	v_mul_f32_e32 v52, v83, v131
	v_fma_f32 v52, v52, v57, v53
	v_mul_f32_e32 v53, 0x3d372713, v52
	v_mul_f32_e32 v53, v52, v53
	v_fma_f32 v53, v52, v53, v52
	v_mul_f32_e32 v53, 0x3f4c422a, v53
	v_add_f32_e32 v53, v53, v53
	v_mul_f32_e32 v53, 0x3fb8aa3b, v53
	v_exp_f32_e32 v53, v53
	s_nop 0
	v_add_f32_e32 v53, 1.0, v53
	v_div_scale_f32 v56, s[4:5], v53, v53, 1.0
	v_rcp_f32_e32 v57, v56
	s_nop 0
	v_fma_f32 v100, -v56, v57, 1.0
	v_fmac_f32_e32 v57, v100, v57
	v_div_scale_f32 v100, vcc, 1.0, v53, 1.0
	v_mul_f32_e32 v101, v100, v57
	v_fma_f32 v102, -v56, v101, v100
	v_fmac_f32_e32 v101, v102, v57
	v_fma_f32 v56, -v56, v101, v100
	v_div_fmas_f32 v56, v56, v57, v101
	v_div_fixup_f32 v53, v56, v53, 1.0
	v_sub_f32_e32 v53, 1.0, v53
	v_mul_f32_e32 v52, v52, v53
	v_bfe_u32 v53, v52, 16, 1
	v_add3_u32 v56, v52, v53, s75
	v_lshlrev_b32_e32 v251, 1, v98
	v_lshl_add_u64 v[52:53], v[98:99], 1, s[64:65]
	v_mov_b32_e32 v217, v56
	v_or_b32_e32 v52, s80, v97
	v_ashrrev_i32_e32 v53, 31, v52
	v_lshlrev_b64 v[52:53], 11, v[52:53]
	v_or_b32_e32 v52, v52, v86
	v_lshl_add_u64 v[56:57], v[52:53], 2, s[60:61]
	v_lshlrev_b32_e32 v252, 1, v52
	v_lshl_add_u64 v[52:53], v[52:53], 1, s[64:65]
	v_mul_f32_e32 v56, v83, v132
	v_fma_f32 v54, v56, v58, v54
	v_mul_f32_e32 v56, 0x3d372713, v54
	v_mul_f32_e32 v56, v54, v56
	v_fma_f32 v56, v54, v56, v54
	v_mul_f32_e32 v56, 0x3f4c422a, v56
	v_add_f32_e32 v56, v56, v56
	v_mul_f32_e32 v56, 0x3fb8aa3b, v56
	v_exp_f32_e32 v56, v56
	s_nop 0
	v_add_f32_e32 v56, 1.0, v56
	v_div_scale_f32 v57, s[4:5], v56, v56, 1.0
	v_rcp_f32_e32 v58, v57
	s_nop 0
	v_fma_f32 v98, -v57, v58, 1.0
	v_fmac_f32_e32 v58, v98, v58
	v_div_scale_f32 v98, vcc, 1.0, v56, 1.0
	v_mul_f32_e32 v99, v98, v58
	v_fma_f32 v100, -v57, v99, v98
	v_fmac_f32_e32 v99, v100, v58
	v_fma_f32 v57, -v57, v99, v98
	v_div_fmas_f32 v57, v57, v58, v99
	v_div_fixup_f32 v56, v57, v56, 1.0
	v_sub_f32_e32 v56, 1.0, v56
	v_mul_f32_e32 v54, v54, v56
	v_bfe_u32 v56, v54, 16, 1
	v_add3_u32 v54, v54, v56, s75
	v_mov_b32_e32 v244, v54
	v_or_b32_e32 v52, s81, v97
	v_ashrrev_i32_e32 v53, 31, v52
	v_lshlrev_b64 v[52:53], 11, v[52:53]
	v_or_b32_e32 v52, v52, v86
	v_lshl_add_u64 v[56:57], v[52:53], 2, s[60:61]
	v_lshlrev_b32_e32 v253, 1, v52
	v_lshl_add_u64 v[52:53], v[52:53], 1, s[64:65]
	v_mul_f32_e32 v54, v83, v133
	v_fmac_f32_e32 v55, v54, v59
	v_mul_f32_e32 v54, 0x3d372713, v55
	v_mul_f32_e32 v54, v55, v54
	v_fma_f32 v54, v55, v54, v55
	v_mul_f32_e32 v54, 0x3f4c422a, v54
	v_add_f32_e32 v54, v54, v54
	v_mul_f32_e32 v54, 0x3fb8aa3b, v54
	v_exp_f32_e32 v54, v54
	s_nop 0
	v_add_f32_e32 v54, 1.0, v54
	v_div_scale_f32 v56, s[4:5], v54, v54, 1.0
	v_rcp_f32_e32 v57, v56
	s_mov_b64 s[4:5], 0
	v_fma_f32 v58, -v56, v57, 1.0
	v_fmac_f32_e32 v57, v58, v57
	v_div_scale_f32 v58, vcc, 1.0, v54, 1.0
	v_mul_f32_e32 v59, v58, v57
	v_fma_f32 v97, -v56, v59, v58
	v_fmac_f32_e32 v59, v97, v57
	v_fma_f32 v56, -v56, v59, v58
	v_div_fmas_f32 v56, v56, v57, v59
	v_div_fixup_f32 v54, v56, v54, 1.0
	v_sub_f32_e32 v54, 1.0, v54
	v_mul_f32_e32 v54, v55, v54
	v_bfe_u32 v55, v54, 16, 1
	v_add3_u32 v54, v54, v55, s75
	v_mov_b32_e32 v245, v54
	s_waitcnt lgkmcnt(0)
	v_mov_b64_e32 v[126:127], v[236:237]
	v_mov_b64_e32 v[128:129], v[238:239]
	v_mov_b64_e32 v[130:131], v[240:241]
	v_mov_b64_e32 v[132:133], v[242:243]
	v_mov_b64_e32 v[156:157], v[172:173]
	v_mov_b64_e32 v[158:159], v[174:175]
	v_mov_b64_e32 v[160:161], v[176:177]
	v_mov_b64_e32 v[162:163], v[178:179]
	v_mov_b64_e32 v[164:165], v[180:181]
	v_mov_b64_e32 v[166:167], v[182:183]
	v_mov_b64_e32 v[168:169], v[184:185]
	v_mov_b64_e32 v[170:171], v[186:187]
	s_and_b64 vcc, exec, s[10:11]
	s_cbranch_vccnz .Lssm3_nofl
	global_store_short_d16_hi v246, v212, s[64:65]
	global_store_short_d16_hi v247, v213, s[64:65]
	global_store_short_d16_hi v248, v214, s[64:65]
	global_store_short_d16_hi v249, v215, s[64:65]
	global_store_short_d16_hi v250, v216, s[64:65]
	global_store_short_d16_hi v251, v217, s[64:65]
	global_store_short_d16_hi v252, v244, s[64:65]
	global_store_short_d16_hi v253, v245, s[64:65]
	s_branch .LBB0_343
.Lssm3_nofl:
	s_cmpk_lg_i32 s53, 0x7f
	s_cbranch_scc0 .LBB0_354
	s_cmpk_gt_i32 s53, 0x7f
	s_mov_b64 s[12:13], 0
	s_cbranch_scc1 .LBB0_355
	s_and_b64 vcc, exec, s[4:5]
	v_lshlrev_b32_e32 v192, 2, v60
	s_cbranch_vccnz .LBB0_356
